# POST gMLP loop: the eight weight-fragment loads per 32-row block issued together with counted waits instead of load-wait-MFMA eight times
# speedup vs baseline: 1.0175x; 1.0029x over previous
; __device__ __forceinline__ unsigned short f2bf(float f) { return (unsigned short)(pk2(f, 0.f) & 0xffffu); }
; __device__ __forceinline__ float bf2f(unsigned short h) { return __uint_as_float(((unsigned)h) << 16); }
; __device__ __forceinline__ float gelu_t(float x) { const float t = x * (-2.3022082f + -0.10294324f * x * x); return x * __builtin_amdgcn_rcpf(1.0f + __builtin_amdgcn_exp2f(t)); }
; __device__ __forceinline__ void post_phase(const Params& p, int l, LAS unsigned char* lds, int tid) {
;     ...
;                 for (int pb = 0; pb < 4; ++pb) {
;                     unsigned short uu[16];
; #pragma unroll
;                     for (int e = 0; e < 16; ++e) uu[e] = px[(size_t)(pb * 32 + (e & 3) + 8 * (e >> 2) + 4 * hi) * NIN + 1280 + col];
;                     f32x16 acc;
; #pragma unroll
;                     for (int e = 0; e < 16; ++e) acc[e] = 0.f;
; #pragma unroll
;                     for (int s = 0; s < 8; ++s) {
;                         const bf16x8 a = *(const bf16x8*)(wsb + (size_t)(pb * 32 + r32) * 128 + 16 * s + 8 * hi);
;                         acc = __builtin_amdgcn_mfma_f32_32x32x16_bf16(a, bfr[s], acc, 0, 0, 0);
;                     }
; #pragma unroll
;                     for (int e = 0; e < 16; ++e) {
;                         const int pp = pb * 32 + (e & 3) + 8 * (e >> 2) + 4 * hi;
;                         MIX[(size_t)(R0 + pp) * KOUT + 768 + col] = f2bf(gelu_t(bf2f(uu[e])) * (acc[e] + bs[pp]));
;                     }
.LBB0_358:
	v_lshl_add_u64 v[102:103], s[88:89], 0, v[100:101]
	global_load_dwordx4 v[0:3], v[102:103], off offset:-128
	global_load_dwordx4 v[136:139], v[102:103], off offset:-96
	global_load_dwordx4 v[160:163], v[102:103], off offset:-64
	global_load_dwordx4 v[164:167], v[102:103], off offset:-32
	global_load_dwordx4 v[168:171], v[102:103], off
	global_load_dwordx4 v[172:175], v[102:103], off offset:32
	global_load_dwordx4 v[176:179], v[102:103], off offset:64
	global_load_dwordx4 v[180:183], v[102:103], off offset:96
	v_lshl_add_u64 v[104:105], s[88:89], 0, v[90:91]
	s_brev_b32 s4, 48
	v_lshl_add_u64 v[150:151], s[88:89], 0, v[98:99]
	v_lshl_add_u64 v[100:101], v[100:101], 0, s[80:81]
	v_lshl_add_u64 v[98:99], v[98:99], 0, s[96:97]
	s_waitcnt vmcnt(7) lgkmcnt(7)
	v_mfma_f32_32x32x16_bf16 v[0:15], v[0:3], v[16:19], 0
	s_waitcnt vmcnt(6) lgkmcnt(6)
	v_mfma_f32_32x32x16_bf16 v[0:15], v[136:139], v[20:23], v[0:15]
	s_waitcnt vmcnt(5) lgkmcnt(5)
	v_mfma_f32_32x32x16_bf16 v[0:15], v[160:163], v[24:27], v[0:15]
	s_waitcnt vmcnt(4) lgkmcnt(4)
	v_mfma_f32_32x32x16_bf16 v[0:15], v[164:167], v[28:31], v[0:15]
	s_waitcnt vmcnt(3) lgkmcnt(3)
	v_mfma_f32_32x32x16_bf16 v[0:15], v[168:171], v[32:35], v[0:15]
	s_waitcnt vmcnt(2) lgkmcnt(2)
	v_mfma_f32_32x32x16_bf16 v[0:15], v[172:175], v[36:39], v[0:15]
	s_waitcnt vmcnt(1) lgkmcnt(1)
	v_mfma_f32_32x32x16_bf16 v[0:15], v[176:179], v[40:43], v[0:15]
	v_add_co_u32_e32 v102, vcc, s4, v104
	s_mov_b32 s4, 0xc001000
	s_nop 0
	v_addc_co_u32_e32 v103, vcc, 0, v105, vcc
	global_load_ushort v89, v[102:103], off offset:2560
	v_add_co_u32_e32 v152, vcc, s22, v150
	s_waitcnt vmcnt(1) lgkmcnt(0)
	v_mfma_f32_32x32x16_bf16 v[0:15], v[180:183], v[44:47], v[0:15]
	v_addc_co_u32_e32 v153, vcc, 0, v151, vcc
	s_waitcnt vmcnt(0)
	v_lshlrev_b32_e32 v89, 16, v89
	v_mul_f32_e32 v102, 0x3dd2d3e8, v89
	v_fma_f32 v102, -v102, v89, s21
	v_mul_f32_e32 v102, v102, v89
	v_exp_f32_e32 v102, v102
	v_add_co_u32_e32 v136, vcc, s4, v104
	s_mov_b32 s4, 0xc002000
	v_add_f32_e32 v102, 1.0, v102
	v_rcp_f32_e32 v102, v102
	v_addc_co_u32_e32 v137, vcc, 0, v105, vcc
	v_mul_f32_e32 v89, v102, v89
	v_lshl_add_u64 v[102:103], v[86:87], 0, s[0:1]
	global_load_dwordx4 v[146:149], v[102:103], off
	s_waitcnt vmcnt(0)
	v_add_f32_e32 v0, v0, v146
	global_load_ushort v146, v[136:137], off offset:2048
	v_add_co_u32_e32 v136, vcc, s4, v104
	s_mov_b32 s4, 0xc003000
	s_nop 0
	v_addc_co_u32_e32 v137, vcc, 0, v105, vcc
	global_load_ushort v156, v[136:137], off offset:1536
	v_add_co_u32_e32 v136, vcc, s4, v104
	s_mov_b32 s4, 0xc007000
	s_nop 0
	v_addc_co_u32_e32 v137, vcc, 0, v105, vcc
	global_load_ushort v157, v[136:137], off offset:1024
	v_add_co_u32_e32 v136, vcc, s4, v104
	s_mov_b32 s4, 0xc008000
	s_nop 0
	v_addc_co_u32_e32 v137, vcc, 0, v105, vcc
	global_load_ushort v158, v[136:137], off offset:2560
	v_add_co_u32_e32 v136, vcc, s4, v104
	s_mov_b32 s4, 0xc009000
	s_nop 0
	v_addc_co_u32_e32 v137, vcc, 0, v105, vcc
	global_load_ushort v145, v[136:137], off offset:2048
	v_add_co_u32_e32 v136, vcc, s4, v104
	s_mov_b32 s4, 0xc00a000
	s_nop 0
	v_addc_co_u32_e32 v137, vcc, 0, v105, vcc
	global_load_ushort v143, v[136:137], off offset:1536
	v_add_co_u32_e32 v136, vcc, s4, v104
	s_mov_b32 s4, 0xc00e000
	s_nop 0
	v_addc_co_u32_e32 v137, vcc, 0, v105, vcc
	global_load_ushort v142, v[136:137], off offset:1024
	v_add_co_u32_e32 v136, vcc, s4, v104
	s_mov_b32 s4, 0xc00f000
	s_nop 0
	v_addc_co_u32_e32 v137, vcc, 0, v105, vcc
	global_load_ushort v141, v[136:137], off offset:2560
	v_add_co_u32_e32 v136, vcc, s4, v104
	s_mov_b32 s4, 0xc010000
	s_nop 0
	v_addc_co_u32_e32 v137, vcc, 0, v105, vcc
	global_load_ushort v140, v[136:137], off offset:2048
	v_add_co_u32_e32 v136, vcc, s4, v104
	s_mov_b32 s4, 0xc011000
	s_nop 0
	v_addc_co_u32_e32 v137, vcc, 0, v105, vcc
	global_load_ushort v139, v[136:137], off offset:1536
	v_add_co_u32_e32 v136, vcc, s4, v104
	s_mov_b32 s4, 0xc015000
	s_nop 0
	v_addc_co_u32_e32 v137, vcc, 0, v105, vcc
	global_load_ushort v138, v[136:137], off offset:1024
	v_add_co_u32_e32 v136, vcc, s4, v104
	s_mov_b32 s4, 0xc016000
	s_nop 0
	v_addc_co_u32_e32 v137, vcc, 0, v105, vcc
	v_add_co_u32_e32 v154, vcc, s4, v104
	s_mov_b32 s4, 0xc017000
	s_nop 0
	v_addc_co_u32_e32 v155, vcc, 0, v105, vcc
	global_load_ushort v137, v[136:137], off offset:2560
	v_mul_f32_e32 v0, v89, v0
	global_load_ushort v136, v[154:155], off offset:2048
	v_add_co_u32_e32 v154, vcc, s4, v104
	s_mov_b32 s4, 0xc018000
	s_nop 0
	v_addc_co_u32_e32 v155, vcc, 0, v105, vcc
	v_add_co_u32_e32 v104, vcc, s4, v104
	v_cvt_pk_bf16_f32 v0, v0, s0
	s_nop 0
	v_addc_co_u32_e32 v105, vcc, 0, v105, vcc
	global_load_ushort v135, v[154:155], off offset:1536
	global_load_ushort v89, v[104:105], off offset:1024
	v_add_f32_e32 v1, v1, v147
	global_store_short v[152:153], v0, off offset:1536
	s_waitcnt vmcnt(15)
	v_lshlrev_b32_e32 v0, 16, v146
	v_mul_f32_e32 v104, 0x3dd2d3e8, v0
	v_fma_f32 v104, -v104, v0, s21
	v_mul_f32_e32 v104, v104, v0
	v_exp_f32_e32 v104, v104
	v_add_f32_e32 v3, v3, v149
	s_mov_b64 s[4:5], 0x1c000
	v_lshl_add_u64 v[90:91], v[90:91], 0, s[4:5]
	v_add_f32_e32 v104, 1.0, v104
	v_rcp_f32_e32 v104, v104
	s_nop 0
	v_mul_f32_e32 v0, v104, v0
	v_mul_f32_e32 v0, v0, v1
	v_cvt_pk_bf16_f32 v0, v0, s0
	global_store_short v[152:153], v0, off offset:3584
	s_waitcnt vmcnt(15)
	v_lshlrev_b32_e32 v0, 16, v156
	v_mul_f32_e32 v1, 0x3dd2d3e8, v0
	v_fma_f32 v1, -v1, v0, s21
	v_mul_f32_e32 v1, v1, v0
	v_exp_f32_e32 v1, v1
	s_nop 0
	v_add_f32_e32 v1, 1.0, v1
	v_rcp_f32_e32 v1, v1
	s_nop 0
	v_mul_f32_e32 v0, v1, v0
	v_add_f32_e32 v1, v2, v148
	v_mul_f32_e32 v0, v0, v1
	v_cvt_pk_bf16_f32 v2, v0, s0
	v_add_co_u32_e32 v0, vcc, s23, v150
	s_nop 1
	v_addc_co_u32_e32 v1, vcc, 0, v151, vcc
	global_store_short v[0:1], v2, off offset:1536
	s_waitcnt vmcnt(15)
; __device__ __forceinline__ unsigned short f2bf(float f) { return (unsigned short)(pk2(f, 0.f) & 0xffffu); }
; __device__ __forceinline__ float bf2f(unsigned short h) { return __uint_as_float(((unsigned)h) << 16); }
; __device__ __forceinline__ float gelu_t(float x) { const float t = x * (-2.3022082f + -0.10294324f * x * x); return x * __builtin_amdgcn_rcpf(1.0f + __builtin_amdgcn_exp2f(t)); }
; __device__ __forceinline__ void post_phase(const Params& p, int l, LAS unsigned char* lds, int tid) {
;     ...
;                 for (int pb = 0; pb < 4; ++pb) {
;                     unsigned short uu[16];
; #pragma unroll
;                     for (int e = 0; e < 16; ++e) uu[e] = px[(size_t)(pb * 32 + (e & 3) + 8 * (e >> 2) + 4 * hi) * NIN + 1280 + col];
;                     f32x16 acc;
; #pragma unroll
;                     for (int e = 0; e < 16; ++e) acc[e] = 0.f;
; #pragma unroll
;                     for (int s = 0; s < 8; ++s) {
;                         const bf16x8 a = *(const bf16x8*)(wsb + (size_t)(pb * 32 + r32) * 128 + 16 * s + 8 * hi);
;                         acc = __builtin_amdgcn_mfma_f32_32x32x16_bf16(a, bfr[s], acc, 0, 0, 0);
;                     }
; #pragma unroll
;                     for (int e = 0; e < 16; ++e) {
;                         const int pp = pb * 32 + (e & 3) + 8 * (e >> 2) + 4 * hi;
;                         MIX[(size_t)(R0 + pp) * KOUT + 768 + col] = f2bf(gelu_t(bf2f(uu[e])) * (acc[e] + bs[pp]));
;                     }
;                 }
;             }
;             __syncthreads();
	v_lshlrev_b32_e32 v2, 16, v157
	v_mul_f32_e32 v104, 0x3dd2d3e8, v2
	v_fma_f32 v104, -v104, v2, s21
	v_mul_f32_e32 v104, v104, v2
	v_exp_f32_e32 v104, v104
	s_nop 0
	v_add_f32_e32 v104, 1.0, v104
	v_rcp_f32_e32 v104, v104
	s_nop 0
	v_mul_f32_e32 v2, v104, v2
	v_mul_f32_e32 v2, v2, v3
	v_cvt_pk_bf16_f32 v2, v2, s0
	global_store_short v[0:1], v2, off offset:3584
	s_waitcnt vmcnt(15)
	v_lshlrev_b32_e32 v0, 16, v158
	v_mul_f32_e32 v1, 0x3dd2d3e8, v0
	v_fma_f32 v1, -v1, v0, s21
	v_mul_f32_e32 v1, v1, v0
	v_exp_f32_e32 v1, v1
	s_nop 0
	v_add_f32_e32 v1, 1.0, v1
	v_rcp_f32_e32 v1, v1
	s_nop 0
	v_mul_f32_e32 v104, v1, v0
	global_load_dwordx4 v[0:3], v[102:103], off offset:32
	s_waitcnt vmcnt(0)
	v_add_f32_e32 v0, v4, v0
	v_mul_f32_e32 v0, v104, v0
	v_lshl_add_u64 v[104:105], s[88:89], 0, v[96:97]
	v_add_co_u32_e32 v146, vcc, s22, v104
	v_cvt_pk_bf16_f32 v0, v0, s0
	s_nop 0
	v_addc_co_u32_e32 v147, vcc, 0, v105, vcc
	global_store_short v[146:147], v0, off offset:1536
	v_lshlrev_b32_e32 v0, 16, v145
	v_mul_f32_e32 v4, 0x3dd2d3e8, v0
	v_fma_f32 v4, -v4, v0, s21
	v_mul_f32_e32 v4, v4, v0
	v_exp_f32_e32 v4, v4
	v_add_f32_e32 v1, v5, v1
	v_add_f32_e32 v3, v7, v3
	v_lshl_add_u64 v[96:97], v[96:97], 0, s[96:97]
	v_add_f32_e32 v4, 1.0, v4
	v_rcp_f32_e32 v4, v4
	s_nop 0
	v_mul_f32_e32 v0, v4, v0
	v_mul_f32_e32 v0, v0, v1
	v_cvt_pk_bf16_f32 v0, v0, s0
	global_store_short v[146:147], v0, off offset:3584
	v_lshlrev_b32_e32 v0, 16, v143
	v_mul_f32_e32 v1, 0x3dd2d3e8, v0
	v_fma_f32 v1, -v1, v0, s21
	v_mul_f32_e32 v1, v1, v0
	v_exp_f32_e32 v1, v1
	s_nop 0
	v_add_f32_e32 v1, 1.0, v1
	v_rcp_f32_e32 v1, v1
	s_nop 0
	v_mul_f32_e32 v0, v1, v0
	v_add_f32_e32 v1, v6, v2
	v_mul_f32_e32 v0, v0, v1
	v_cvt_pk_bf16_f32 v2, v0, s0
	v_add_co_u32_e32 v0, vcc, s23, v104
	s_nop 1
	v_addc_co_u32_e32 v1, vcc, 0, v105, vcc
	global_store_short v[0:1], v2, off offset:1536
	v_lshlrev_b32_e32 v2, 16, v142
	v_mul_f32_e32 v4, 0x3dd2d3e8, v2
	v_fma_f32 v4, -v4, v2, s21
	v_mul_f32_e32 v4, v4, v2
	v_exp_f32_e32 v4, v4
	s_nop 0
	v_add_f32_e32 v4, 1.0, v4
	v_rcp_f32_e32 v4, v4
	s_nop 0
	v_mul_f32_e32 v2, v4, v2
	v_mul_f32_e32 v2, v2, v3
	v_cvt_pk_bf16_f32 v2, v2, s0
	global_store_short v[0:1], v2, off offset:3584
	v_lshlrev_b32_e32 v0, 16, v141
	v_mul_f32_e32 v1, 0x3dd2d3e8, v0
	v_fma_f32 v1, -v1, v0, s21
	v_mul_f32_e32 v1, v1, v0
	v_exp_f32_e32 v1, v1
	s_nop 0
	v_add_f32_e32 v1, 1.0, v1
	v_rcp_f32_e32 v1, v1
	s_nop 0
	v_mul_f32_e32 v4, v1, v0
	global_load_dwordx4 v[0:3], v[102:103], off offset:64
	s_waitcnt vmcnt(0)
	v_add_f32_e32 v0, v8, v0
	v_mul_f32_e32 v0, v4, v0
	v_lshl_add_u64 v[4:5], s[88:89], 0, v[94:95]
	v_add_co_u32_e32 v6, vcc, s22, v4
	v_cvt_pk_bf16_f32 v0, v0, s0
	s_nop 0
	v_addc_co_u32_e32 v7, vcc, 0, v5, vcc
	global_store_short v[6:7], v0, off offset:1536
	v_lshlrev_b32_e32 v0, 16, v140
	v_mul_f32_e32 v8, 0x3dd2d3e8, v0
	v_fma_f32 v8, -v8, v0, s21
	v_mul_f32_e32 v8, v8, v0
	v_exp_f32_e32 v8, v8
	v_add_f32_e32 v1, v9, v1
	v_add_f32_e32 v3, v11, v3
	v_lshl_add_u64 v[94:95], v[94:95], 0, s[96:97]
	v_add_f32_e32 v8, 1.0, v8
	v_rcp_f32_e32 v8, v8
	s_nop 0
	v_mul_f32_e32 v0, v8, v0
	v_mul_f32_e32 v0, v0, v1
	v_cvt_pk_bf16_f32 v0, v0, s0
	global_store_short v[6:7], v0, off offset:3584
	v_lshlrev_b32_e32 v0, 16, v139
	v_mul_f32_e32 v1, 0x3dd2d3e8, v0
	v_fma_f32 v1, -v1, v0, s21
	v_mul_f32_e32 v1, v1, v0
	v_exp_f32_e32 v1, v1
	s_nop 0
	v_add_f32_e32 v1, 1.0, v1
	v_rcp_f32_e32 v1, v1
	s_nop 0
	v_mul_f32_e32 v0, v1, v0
	v_add_f32_e32 v1, v10, v2
	v_mul_f32_e32 v0, v0, v1
	v_cvt_pk_bf16_f32 v2, v0, s0
	v_add_co_u32_e32 v0, vcc, s23, v4
	s_nop 1
	v_addc_co_u32_e32 v1, vcc, 0, v5, vcc
	global_store_short v[0:1], v2, off offset:1536
	v_lshlrev_b32_e32 v2, 16, v138
	v_mul_f32_e32 v4, 0x3dd2d3e8, v2
	v_fma_f32 v4, -v4, v2, s21
	v_mul_f32_e32 v4, v4, v2
	v_exp_f32_e32 v4, v4
	s_nop 0
	v_add_f32_e32 v4, 1.0, v4
	v_rcp_f32_e32 v4, v4
	s_nop 0
	v_mul_f32_e32 v2, v4, v2
	v_mul_f32_e32 v2, v2, v3
	v_cvt_pk_bf16_f32 v2, v2, s0
	global_store_short v[0:1], v2, off offset:3584
	v_lshlrev_b32_e32 v0, 16, v137
	v_mul_f32_e32 v1, 0x3dd2d3e8, v0
	v_fma_f32 v1, -v1, v0, s21
	v_mul_f32_e32 v1, v1, v0
	v_exp_f32_e32 v1, v1
	s_nop 0
	v_add_f32_e32 v1, 1.0, v1
	v_rcp_f32_e32 v1, v1
	s_nop 0
	v_mul_f32_e32 v4, v1, v0
	global_load_dwordx4 v[0:3], v[102:103], off offset:96
	s_waitcnt vmcnt(0)
	v_add_f32_e32 v0, v12, v0
	v_mul_f32_e32 v0, v4, v0
	v_lshl_add_u64 v[4:5], s[88:89], 0, v[92:93]
	v_add_co_u32_e32 v6, vcc, s22, v4
	v_cvt_pk_bf16_f32 v0, v0, s0
	s_nop 0
	v_addc_co_u32_e32 v7, vcc, 0, v5, vcc
	global_store_short v[6:7], v0, off offset:1536
	v_lshlrev_b32_e32 v0, 16, v136
	v_mul_f32_e32 v8, 0x3dd2d3e8, v0
	v_fma_f32 v8, -v8, v0, s21
	v_mul_f32_e32 v8, v8, v0
	v_exp_f32_e32 v8, v8
	v_add_f32_e32 v1, v13, v1
	v_add_f32_e32 v3, v15, v3
	v_lshl_add_u64 v[92:93], v[92:93], 0, s[96:97]
	v_add_f32_e32 v8, 1.0, v8
	v_rcp_f32_e32 v8, v8
	s_nop 0
	v_mul_f32_e32 v0, v8, v0
	v_mul_f32_e32 v0, v0, v1
	v_cvt_pk_bf16_f32 v0, v0, s0
	global_store_short v[6:7], v0, off offset:3584
	v_lshlrev_b32_e32 v0, 16, v135
	v_mul_f32_e32 v1, 0x3dd2d3e8, v0
	v_fma_f32 v1, -v1, v0, s21
	v_mul_f32_e32 v1, v1, v0
	v_exp_f32_e32 v1, v1
	s_nop 0
	v_add_f32_e32 v1, 1.0, v1
	v_rcp_f32_e32 v1, v1
	s_nop 0
	v_mul_f32_e32 v0, v1, v0
	v_add_f32_e32 v1, v14, v2
	v_mul_f32_e32 v0, v0, v1
	v_cvt_pk_bf16_f32 v2, v0, s0
	v_add_co_u32_e32 v0, vcc, s23, v4
	s_nop 1
	v_addc_co_u32_e32 v1, vcc, 0, v5, vcc
	global_store_short v[0:1], v2, off offset:1536
	v_lshlrev_b32_e32 v2, 16, v89
	v_mul_f32_e32 v4, 0x3dd2d3e8, v2
	v_fma_f32 v4, -v4, v2, s21
	v_mul_f32_e32 v4, v4, v2
	v_exp_f32_e32 v4, v4
	s_nop 0
	v_add_f32_e32 v4, 1.0, v4
	v_rcp_f32_e32 v4, v4
	s_nop 0
	v_mul_f32_e32 v2, v4, v2
	v_mul_f32_e32 v2, v2, v3
	v_cvt_pk_bf16_f32 v2, v2, s0
	s_add_u32 s0, s0, 0x80
	s_addc_u32 s1, s1, 0
	s_cmpk_eq_i32 s0, 0x200
	global_store_short v[0:1], v2, off offset:3584
	s_cbranch_scc0 .LBB0_358
	v_readlane_b32 s42, v253, 24
	s_mov_b64 s[0:1], 0
	v_readlane_b32 s43, v253, 25
	s_barrier
